# diff-attn loop: common-path trims (rescale path out of line behind one scalar test, canonicalising max pairs collapsed, running sum in place) and one lgkmcnt wait per fragment pair in the QK ring; on
# speedup vs baseline: 1.0091x; 1.0015x over previous
; #define SBAR() __builtin_amdgcn_sched_barrier(0)
; __device__ __forceinline__ int v_rd_base(int lane) { return ((lane & 3) << 3) | (((lane >> 2) & 3) << 6) | (((lane >> 4) & 1) << 5) | (((lane >> 5) & 1) << 8); }
; #define A3_BAR() do { asm volatile("s_waitcnt vmcnt(0) lgkmcnt(0)" ::: "memory"); __builtin_amdgcn_s_barrier(); asm volatile("" ::: "memory"); } while (0)
; #define lane lane_id()
; template <int KB, bool SK>
; __device__ __forceinline__ void qkt(f32x16& p0, f32x16& p1, const char* K_lds, int r32, int hi, const bf16x8* qr, bool act) {
;     if (SK && !act) return;
;     p0 = f32x16{}; p1 = f32x16{};
;     const char* kb[4];
; #pragma unroll
;     for (int dd = 0; dd < 4; ++dd) kb[dd] = K_lds + KB * SHM_K + KSWZ(r32, (dd * 16 + hi * 8) * 2);
; #pragma unroll
;     for (int d0 = 0; d0 < 8; ++d0) { const char* a = kb[d0 & 3] + (d0 >> 2) * 128;
;         bf16x8 b0 = *reinterpret_cast<const bf16x8*>(a);
;         bf16x8 b1 = *reinterpret_cast<const bf16x8*>(a + 32 * 256);
;         p0 = __builtin_amdgcn_mfma_f32_32x32x16_bf16(b0, qr[d0], p0, 0, 0, 0);
;         p1 = __builtin_amdgcn_mfma_f32_32x32x16_bf16(b1, qr[d0], p1, 0, 0, 0); }
; }
; __device__ __forceinline__ void attn_block3(const BlockRef& cur, char* lds, const int wid) {
;     ...
;     A3_DMA(0);
;     A3_BAR();
;     float m_reg = -1e30f, l_reg = 0; f32x16 o[4] = {}, o2[4] = {};
;     const int vbase = (int)(uintptr_t)V_lds + v_rd_base(lane);
;     for (int t = 0; t < NT; ++t) {
;         f32x16 p0, p1; float mn, alpha; bf16x8 pa0, pa1, pa2, pa3;
;         const int kb = t * KVBLK;
;         qkt<0, false>(p0, p1, K_lds + (t & 1) * SHM_K, r32, hi, qr, true);
;         SBAR(); if (t + 1 < NT) A3_DMA(t + 1);
.LBB0_449:
	s_and_b32 s95, s93, 1
	s_lshl_b32 s7, s95, 14
	s_add_i32 s7, s7, 0x10000
	v_add3_u32 v0, s7, v242, v240
	ds_read_b128 v[2:5], v0
	ds_read_b128 v[10:13], v0 offset:8192
	v_add3_u32 v6, s7, v243, v240
	ds_read_b128 v[176:179], v6
	ds_read_b128 v[180:183], v6 offset:8192
	v_add3_u32 v7, s7, v244, v240
	ds_read_b128 v[184:187], v7
	ds_read_b128 v[188:191], v7 offset:8192
	s_mov_b32 s6, s93
	s_waitcnt lgkmcnt(4)
	v_mfma_f32_32x32x16_bf16 v[160:175], v[2:5], v[192:195], 0
	v_add3_u32 v8, s7, v245, v240
	ds_read_b128 v[2:5], v8
	v_mfma_f32_32x32x16_bf16 v[144:159], v[10:13], v[192:195], 0
	ds_read_b128 v[10:13], v8 offset:8192
	s_waitcnt lgkmcnt(4)
	v_mfma_f32_32x32x16_bf16 v[160:175], v[176:179], v[196:199], v[160:175]
	ds_read_b128 v[176:179], v0 offset:128
	v_mfma_f32_32x32x16_bf16 v[144:159], v[180:183], v[196:199], v[144:159]
	ds_read_b128 v[180:183], v0 offset:8320
	s_waitcnt lgkmcnt(4)
	v_mfma_f32_32x32x16_bf16 v[160:175], v[184:187], v[200:203], v[160:175]
	ds_read_b128 v[184:187], v6 offset:128
	v_mfma_f32_32x32x16_bf16 v[144:159], v[188:191], v[200:203], v[144:159]
	ds_read_b128 v[188:191], v6 offset:8320
	s_waitcnt lgkmcnt(4)
	v_mfma_f32_32x32x16_bf16 v[160:175], v[2:5], v[204:207], v[160:175]
	ds_read_b128 v[2:5], v7 offset:128
	v_mfma_f32_32x32x16_bf16 v[144:159], v[10:13], v[204:207], v[144:159]
	ds_read_b128 v[10:13], v7 offset:8320
	s_waitcnt lgkmcnt(4)
	v_mfma_f32_32x32x16_bf16 v[160:175], v[176:179], v[208:211], v[160:175]
	ds_read_b128 v[176:179], v8 offset:128
	v_mfma_f32_32x32x16_bf16 v[144:159], v[180:183], v[208:211], v[144:159]
	ds_read_b128 v[180:183], v8 offset:8320
	s_waitcnt lgkmcnt(4)
	v_mfma_f32_32x32x16_bf16 v[160:175], v[184:187], v[212:215], v[160:175]
	v_mfma_f32_32x32x16_bf16 v[144:159], v[188:191], v[212:215], v[144:159]
	s_waitcnt lgkmcnt(2)
	v_mfma_f32_32x32x16_bf16 v[160:175], v[2:5], v[216:219], v[160:175]
	v_mfma_f32_32x32x16_bf16 v[144:159], v[10:13], v[216:219], v[144:159]
	s_waitcnt lgkmcnt(0)
	v_mfma_f32_32x32x16_bf16 v[160:175], v[176:179], v[220:223], v[160:175]
	v_mfma_f32_32x32x16_bf16 v[144:159], v[180:183], v[220:223], v[144:159]
	s_add_i32 s93, s93, 1
	s_cmp_ge_u32 s6, s87
	s_cbranch_scc1 .LBB0_451
	s_and_b32 s6, s93, 1
	s_lshl_b32 s7, s6, 14
	s_add_i32 s7, s83, s7
	s_lshl_b32 s6, s6, 15
	s_mov_b32 m0, s7
	s_add_i32 s6, s82, s6
	global_load_lds_dwordx4 v228, s[68:69]
	s_mov_b32 m0, s6
	s_add_i32 s20, s6, 0x4000
	global_load_lds_dwordx4 v224, s[98:99]
	s_mov_b32 m0, s20
	s_nop 0
	global_load_lds_dwordx4 v224, s[100:101]
	s_add_i32 m0, s7, 0x400
	s_nop 0
	global_load_lds_dwordx4 v230, s[68:69]
	s_add_i32 m0, s6, 0x400
	s_nop 0
	global_load_lds_dwordx4 v225, s[98:99]
	s_add_i32 m0, s6, 0x4400
	s_nop 0
	global_load_lds_dwordx4 v225, s[100:101]

; __device__ __forceinline__ void partialSM(f32x16& p0, f32x16& p1, float& m_reg, float& mn, float& alpha) {
;     float pmax = p0[0];
; #pragma unroll
;     for (int r = 1; r < 16; ++r) pmax = fmaxf(pmax, p0[r]);
; #pragma unroll
;     for (int r = 0; r < 16; ++r) pmax = fmaxf(pmax, p1[r]);
;     { auto rr = __builtin_amdgcn_permlane32_swap(__float_as_uint(pmax), __float_as_uint(pmax), false, false);
;       pmax = fmaxf(__uint_as_float(rr[0]), __uint_as_float(rr[1])); }
;     constexpr float C2 = 1.4426950408889634f * SM_SCALE;
;     if (__builtin_expect(__all((pmax - m_reg) * SM_SCALE <= THR), 1)) { mn = m_reg; alpha = 1.f; }
;     else { mn = fmaxf(m_reg, pmax); alpha = __builtin_amdgcn_exp2f((m_reg - mn) * C2); m_reg = mn; }
;     const float mnL = -mn * C2;
; #pragma unroll
;     for (int r = 0; r < 16; ++r) p0[r] = fmaf(p0[r], C2, mnL);
; #pragma unroll
;     for (int r = 0; r < 16; ++r) p1[r] = fmaf(p1[r], C2, mnL);
; #pragma unroll
;     for (int r = 0; r < 16; ++r) p0[r] = __builtin_amdgcn_exp2f(p0[r]);
; }
; __device__ __forceinline__ void finishSM(f32x16& p0, f32x16& p1, float alpha, float& l_reg, bf16x8& pa0, bf16x8& pa1, bf16x8& pa2, bf16x8& pa3) {
; #pragma unroll
;     for (int r = 0; r < 16; ++r) p1[r] = __builtin_amdgcn_exp2f(p1[r]);
;     float ps = 0;
; #pragma unroll
;     for (int r = 0; r < 16; ++r) ps += p0[r];
; #pragma unroll
;     for (int r = 0; r < 16; ++r) ps += p1[r];
;     { auto rr = __builtin_amdgcn_permlane32_swap(__float_as_uint(ps), __float_as_uint(ps), false, false);
;       ps = __uint_as_float(rr[0]) + __uint_as_float(rr[1]); }
;     l_reg = l_reg * alpha + ps;
;     PK4(p0, 0, pa0); PK4(p0, 8, pa1); PK4(p1, 0, pa2); PK4(p1, 8, pa3);
; }
; __device__ __forceinline__ void pv_tile2(f32x16* o, f32x16* o2, int vb0, bf16x8 pa0, bf16x8 pa1, bf16x8 pa2, bf16x8 pa3) {
.LBB0_485:
	s_nop 3
	v_max_f32_e32 v0, v160, v161
	v_max3_f32 v0, v0, v162, v163
	v_max3_f32 v0, v0, v164, v165
	v_max3_f32 v0, v0, v166, v167
	v_max3_f32 v0, v0, v168, v169
	v_max3_f32 v0, v0, v170, v171
	v_max3_f32 v0, v0, v172, v173
	v_max3_f32 v0, v0, v174, v175
	v_max3_f32 v0, v0, v144, v145
	v_max3_f32 v0, v0, v146, v147
	v_max3_f32 v0, v0, v148, v149
	v_max3_f32 v0, v0, v150, v151
	v_max3_f32 v0, v0, v152, v153
	v_max3_f32 v0, v0, v154, v155
	v_max3_f32 v0, v0, v156, v157
	v_max3_f32 v0, v0, v158, v159
	v_mov_b32_e32 v2, v0
	s_nop 1
	v_permlane32_swap_b32_e32 v0, v2
	v_max_f32_e32 v0, v0, v2
	v_sub_f32_e32 v2, v0, v249
	v_mul_f32_e32 v2, 0x3db504f3, v2
	v_cmp_ge_f32_e32 vcc, 0x41000000, v2
	s_cmp_eq_u64 vcc, exec
	s_cbranch_scc0 .Ldiff_slow
	v_mov_b32_e32 v0, 1.0
.Ldiff_join:
	v_mul_f32_e32 v2, 0xbe0293ee, v249
	v_fmamk_f32 v3, v160, 0x3e0293ee, v2
	v_fmamk_f32 v4, v161, 0x3e0293ee, v2
	v_exp_f32_e32 v3, v3
	v_fmamk_f32 v5, v162, 0x3e0293ee, v2
	v_exp_f32_e32 v4, v4
	v_fmamk_f32 v6, v163, 0x3e0293ee, v2
	v_exp_f32_e32 v5, v5
	v_fmamk_f32 v7, v164, 0x3e0293ee, v2
	v_fmamk_f32 v8, v165, 0x3e0293ee, v2
	v_fmamk_f32 v9, v166, 0x3e0293ee, v2
	v_fmamk_f32 v10, v167, 0x3e0293ee, v2
	v_fmamk_f32 v11, v168, 0x3e0293ee, v2
	v_fmamk_f32 v12, v169, 0x3e0293ee, v2
	v_fmamk_f32 v13, v170, 0x3e0293ee, v2
	v_fmamk_f32 v14, v171, 0x3e0293ee, v2
	v_fmamk_f32 v15, v172, 0x3e0293ee, v2
	v_fmamk_f32 v160, v173, 0x3e0293ee, v2
	v_fmamk_f32 v161, v174, 0x3e0293ee, v2
	v_fmamk_f32 v162, v175, 0x3e0293ee, v2
	v_fmamk_f32 v144, v144, 0x3e0293ee, v2
	v_fmamk_f32 v145, v145, 0x3e0293ee, v2
	v_fmamk_f32 v146, v146, 0x3e0293ee, v2
	v_fmamk_f32 v147, v147, 0x3e0293ee, v2
	v_fmamk_f32 v148, v148, 0x3e0293ee, v2
	v_fmamk_f32 v149, v149, 0x3e0293ee, v2
	v_fmamk_f32 v150, v150, 0x3e0293ee, v2
	v_fmamk_f32 v151, v151, 0x3e0293ee, v2
	v_fmamk_f32 v152, v152, 0x3e0293ee, v2
	v_fmamk_f32 v153, v153, 0x3e0293ee, v2
	v_fmamk_f32 v154, v154, 0x3e0293ee, v2
	v_fmamk_f32 v155, v155, 0x3e0293ee, v2
	v_fmamk_f32 v156, v156, 0x3e0293ee, v2
	v_fmamk_f32 v157, v157, 0x3e0293ee, v2
	v_fmamk_f32 v158, v158, 0x3e0293ee, v2
	v_fmac_f32_e32 v2, 0x3e0293ee, v159
	v_exp_f32_e32 v159, v6
	v_exp_f32_e32 v163, v7
	v_exp_f32_e32 v165, v2
	v_add_f32_e32 v2, 0, v3
	v_exp_f32_e32 v8, v8
	v_add_f32_e32 v2, v4, v2
	v_exp_f32_e32 v9, v9
	v_add_f32_e32 v2, v5, v2
	v_exp_f32_e32 v10, v10
	v_add_f32_e32 v2, v159, v2
	v_exp_f32_e32 v11, v11
	v_add_f32_e32 v2, v163, v2
	v_exp_f32_e32 v12, v12
	v_add_f32_e32 v2, v8, v2
	v_exp_f32_e32 v13, v13
	v_add_f32_e32 v2, v9, v2
	v_exp_f32_e32 v164, v14
	v_add_f32_e32 v2, v10, v2
	v_exp_f32_e32 v15, v15
	v_add_f32_e32 v2, v11, v2
	v_exp_f32_e32 v160, v160
	v_add_f32_e32 v2, v12, v2
	v_exp_f32_e32 v161, v161
	v_add_f32_e32 v2, v13, v2
	v_exp_f32_e32 v162, v162
	v_add_f32_e32 v2, v164, v2
	v_exp_f32_e32 v144, v144
	v_add_f32_e32 v2, v15, v2
	v_exp_f32_e32 v145, v145
	v_add_f32_e32 v2, v160, v2
	v_exp_f32_e32 v146, v146
	v_add_f32_e32 v2, v161, v2
	v_exp_f32_e32 v147, v147
	v_add_f32_e32 v2, v162, v2
	v_exp_f32_e32 v148, v148
	v_add_f32_e32 v2, v144, v2
	v_exp_f32_e32 v149, v149
	v_add_f32_e32 v2, v145, v2
	v_exp_f32_e32 v150, v150
	v_add_f32_e32 v2, v146, v2
	v_exp_f32_e32 v151, v151
	v_add_f32_e32 v2, v147, v2
	v_exp_f32_e32 v152, v152
	v_add_f32_e32 v2, v148, v2
	v_exp_f32_e32 v153, v153
	v_add_f32_e32 v2, v149, v2
	v_exp_f32_e32 v154, v154
	v_add_f32_e32 v2, v150, v2
	v_exp_f32_e32 v155, v155
	v_add_f32_e32 v2, v151, v2
	v_exp_f32_e32 v156, v156
	v_add_f32_e32 v2, v152, v2
	v_exp_f32_e32 v157, v157
	v_add_f32_e32 v2, v153, v2
	v_exp_f32_e32 v158, v158
	v_add_f32_e32 v2, v154, v2
	v_add_f32_e32 v2, v155, v2
	v_add_f32_e32 v2, v156, v2
	v_add_f32_e32 v2, v157, v2
	v_add_f32_e32 v2, v158, v2
	v_add_f32_e32 v2, v165, v2
	v_mov_b32_e32 v6, v2
	s_nop 1
	v_permlane32_swap_b32_e32 v2, v6
	v_add_f32_e32 v14, v2, v6
	v_fma_f32 v250, v250, v0, v14
	v_cvt_pk_bf16_f32 v6, v3, v4
	v_cvt_pk_bf16_f32 v7, v5, v159
	v_cvt_pk_bf16_f32 v8, v163, v8
	v_cvt_pk_bf16_f32 v9, v9, v10
	v_cvt_pk_bf16_f32 v10, v11, v12
	v_cvt_pk_bf16_f32 v11, v13, v164
	v_cvt_pk_bf16_f32 v12, v15, v160
	v_cvt_pk_bf16_f32 v13, v161, v162
	v_cvt_pk_bf16_f32 v144, v144, v145
	v_cvt_pk_bf16_f32 v145, v146, v147
	v_cvt_pk_bf16_f32 v146, v148, v149
	v_cvt_pk_bf16_f32 v147, v150, v151
	v_cvt_pk_bf16_f32 v2, v152, v153
	v_cvt_pk_bf16_f32 v3, v154, v155
	v_cvt_pk_bf16_f32 v4, v156, v157
	v_cvt_pk_bf16_f32 v5, v158, v165
	s_nop 0
	v_permlane32_swap_b32_e32 v6, v8
	v_permlane32_swap_b32_e32 v7, v9
	v_permlane32_swap_b32_e32 v10, v12
	v_permlane32_swap_b32_e32 v11, v13
	v_permlane32_swap_b32_e32 v144, v146
	v_permlane32_swap_b32_e32 v145, v147
	v_permlane32_swap_b32_e32 v2, v4
	v_permlane32_swap_b32_e32 v3, v5
	v_lshl_add_u32 v0, s95, 15, v246
	ds_read_b64_tr_b16 v[148:149], v0 offset:0
	ds_read_b64_tr_b16 v[150:151], v0 offset:0x800
	ds_read_b64_tr_b16 v[152:153], v0 offset:0x4000
	ds_read_b64_tr_b16 v[154:155], v0 offset:0x4800
	ds_read_b64_tr_b16 v[156:157], v0 offset:0x1000
	ds_read_b64_tr_b16 v[158:159], v0 offset:0x1800
	ds_read_b64_tr_b16 v[160:161], v0 offset:0x5000
	ds_read_b64_tr_b16 v[162:163], v0 offset:0x5800
	ds_read_b64_tr_b16 v[164:165], v0 offset:0x2000
	ds_read_b64_tr_b16 v[166:167], v0 offset:0x2800
	ds_read_b64_tr_b16 v[168:169], v0 offset:0x6000
	ds_read_b64_tr_b16 v[170:171], v0 offset:0x6800
	ds_read_b64_tr_b16 v[172:173], v0 offset:0x3000
	ds_read_b64_tr_b16 v[174:175], v0 offset:0x3800
	ds_read_b64_tr_b16 v[176:177], v0 offset:0x7000
	ds_read_b64_tr_b16 v[178:179], v0 offset:0x7800
	s_waitcnt lgkmcnt(0)
; #define A3_BAR() do { asm volatile("s_waitcnt vmcnt(0) lgkmcnt(0)" ::: "memory"); __builtin_amdgcn_s_barrier(); asm volatile("" ::: "memory"); } while (0)
; __device__ __forceinline__ void pv_tile2(f32x16* o, f32x16* o2, int vb0, bf16x8 pa0, bf16x8 pa1, bf16x8 pa2, bf16x8 pa3) {
;     ...
;     PV2_D0(0); PV2_D0(1); PV2_D0(2); PV2_D0(3);
;     ...
; }
; __device__ __forceinline__ void attn_block3(const BlockRef& cur, char* lds, const int wid) {
;     ...
;         A3_BAR();
	s_nop 0
	v_mfma_f32_32x32x16_bf16 v[112:127], v[6:9], v[148:151], v[112:127]
	ds_read_b64_tr_b16 v[148:149], v0 offset:0x200
	ds_read_b64_tr_b16 v[150:151], v0 offset:0xa00
	v_mfma_f32_32x32x16_bf16 v[128:143], v[6:9], v[152:155], v[128:143]
	ds_read_b64_tr_b16 v[152:153], v0 offset:0x4200
	ds_read_b64_tr_b16 v[154:155], v0 offset:0x4a00
	v_mfma_f32_32x32x16_bf16 v[112:127], v[10:13], v[156:159], v[112:127]
	ds_read_b64_tr_b16 v[156:157], v0 offset:0x1200
	ds_read_b64_tr_b16 v[158:159], v0 offset:0x1a00
	v_mfma_f32_32x32x16_bf16 v[128:143], v[10:13], v[160:163], v[128:143]
	ds_read_b64_tr_b16 v[160:161], v0 offset:0x5200
	ds_read_b64_tr_b16 v[162:163], v0 offset:0x5a00
	v_mfma_f32_32x32x16_bf16 v[112:127], v[144:147], v[164:167], v[112:127]
	ds_read_b64_tr_b16 v[164:165], v0 offset:0x2200
	ds_read_b64_tr_b16 v[166:167], v0 offset:0x2a00
	v_mfma_f32_32x32x16_bf16 v[128:143], v[144:147], v[168:171], v[128:143]
	ds_read_b64_tr_b16 v[168:169], v0 offset:0x6200
	ds_read_b64_tr_b16 v[170:171], v0 offset:0x6a00
	v_mfma_f32_32x32x16_bf16 v[112:127], v[2:5], v[172:175], v[112:127]
	ds_read_b64_tr_b16 v[172:173], v0 offset:0x3200
	ds_read_b64_tr_b16 v[174:175], v0 offset:0x3a00
	v_mfma_f32_32x32x16_bf16 v[128:143], v[2:5], v[176:179], v[128:143]
	ds_read_b64_tr_b16 v[176:177], v0 offset:0x7200
	ds_read_b64_tr_b16 v[178:179], v0 offset:0x7a00
	s_waitcnt lgkmcnt(0)
	v_mfma_f32_32x32x16_bf16 v[80:95], v[6:9], v[148:151], v[80:95]
	ds_read_b64_tr_b16 v[148:149], v0 offset:0x400
	ds_read_b64_tr_b16 v[150:151], v0 offset:0xc00
	v_mfma_f32_32x32x16_bf16 v[96:111], v[6:9], v[152:155], v[96:111]
	ds_read_b64_tr_b16 v[152:153], v0 offset:0x4400
	ds_read_b64_tr_b16 v[154:155], v0 offset:0x4c00
	v_mfma_f32_32x32x16_bf16 v[80:95], v[10:13], v[156:159], v[80:95]
	ds_read_b64_tr_b16 v[156:157], v0 offset:0x1400
	ds_read_b64_tr_b16 v[158:159], v0 offset:0x1c00
	v_mfma_f32_32x32x16_bf16 v[96:111], v[10:13], v[160:163], v[96:111]
	ds_read_b64_tr_b16 v[160:161], v0 offset:0x5400
	ds_read_b64_tr_b16 v[162:163], v0 offset:0x5c00
	v_mfma_f32_32x32x16_bf16 v[80:95], v[144:147], v[164:167], v[80:95]
	ds_read_b64_tr_b16 v[164:165], v0 offset:0x2400
	ds_read_b64_tr_b16 v[166:167], v0 offset:0x2c00
	v_mfma_f32_32x32x16_bf16 v[96:111], v[144:147], v[168:171], v[96:111]
	ds_read_b64_tr_b16 v[168:169], v0 offset:0x6400
	ds_read_b64_tr_b16 v[170:171], v0 offset:0x6c00
	v_mfma_f32_32x32x16_bf16 v[80:95], v[2:5], v[172:175], v[80:95]
	ds_read_b64_tr_b16 v[172:173], v0 offset:0x3400
	ds_read_b64_tr_b16 v[174:175], v0 offset:0x3c00
	v_mfma_f32_32x32x16_bf16 v[96:111], v[2:5], v[176:179], v[96:111]
	ds_read_b64_tr_b16 v[176:177], v0 offset:0x7400
	ds_read_b64_tr_b16 v[178:179], v0 offset:0x7c00
	s_waitcnt lgkmcnt(0)
	v_mfma_f32_32x32x16_bf16 v[48:63], v[6:9], v[148:151], v[48:63]
	ds_read_b64_tr_b16 v[148:149], v0 offset:0x600
	ds_read_b64_tr_b16 v[150:151], v0 offset:0xe00
	v_mfma_f32_32x32x16_bf16 v[64:79], v[6:9], v[152:155], v[64:79]
	ds_read_b64_tr_b16 v[152:153], v0 offset:0x4600
	ds_read_b64_tr_b16 v[154:155], v0 offset:0x4e00
	v_mfma_f32_32x32x16_bf16 v[48:63], v[10:13], v[156:159], v[48:63]
	ds_read_b64_tr_b16 v[156:157], v0 offset:0x1600
	ds_read_b64_tr_b16 v[158:159], v0 offset:0x1e00
	v_mfma_f32_32x32x16_bf16 v[64:79], v[10:13], v[160:163], v[64:79]
	ds_read_b64_tr_b16 v[160:161], v0 offset:0x5600
	ds_read_b64_tr_b16 v[162:163], v0 offset:0x5e00
	v_mfma_f32_32x32x16_bf16 v[48:63], v[144:147], v[164:167], v[48:63]
	ds_read_b64_tr_b16 v[164:165], v0 offset:0x2600
	ds_read_b64_tr_b16 v[166:167], v0 offset:0x2e00
	v_mfma_f32_32x32x16_bf16 v[64:79], v[144:147], v[168:171], v[64:79]
	ds_read_b64_tr_b16 v[168:169], v0 offset:0x6600
	ds_read_b64_tr_b16 v[170:171], v0 offset:0x6e00
	v_mfma_f32_32x32x16_bf16 v[48:63], v[2:5], v[172:175], v[48:63]
	ds_read_b64_tr_b16 v[172:173], v0 offset:0x3600
	ds_read_b64_tr_b16 v[174:175], v0 offset:0x3e00
	v_mfma_f32_32x32x16_bf16 v[64:79], v[2:5], v[176:179], v[64:79]
	ds_read_b64_tr_b16 v[176:177], v0 offset:0x7600
	ds_read_b64_tr_b16 v[178:179], v0 offset:0x7e00
	s_waitcnt lgkmcnt(0)
	v_mfma_f32_32x32x16_bf16 v[16:31], v[6:9], v[148:151], v[16:31]
	s_waitcnt vmcnt(0) lgkmcnt(0)
	s_barrier
	s_add_u32 s68, s68, 0x4000
	s_addc_u32 s69, s69, 0
	s_add_u32 s98, s98, 0x4000
	s_addc_u32 s99, s99, 0
	s_add_u32 s100, s100, 0x4000
	s_addc_u32 s101, s101, 0
	s_add_i32 s90, s90, 64
	v_add_u32_e32 v247, 0xffffff00, v247
	v_mfma_f32_32x32x16_bf16 v[32:47], v[6:9], v[152:155], v[32:47]
	v_subrev_u32_e32 v248, 64, v248
	s_cmp_eq_u32 s88, s93
	v_mfma_f32_32x32x16_bf16 v[16:31], v[10:13], v[156:159], v[16:31]
	v_mfma_f32_32x32x16_bf16 v[32:47], v[10:13], v[160:163], v[32:47]
	v_mfma_f32_32x32x16_bf16 v[16:31], v[144:147], v[164:167], v[16:31]
	v_mfma_f32_32x32x16_bf16 v[32:47], v[144:147], v[168:171], v[32:47]
	v_mfma_f32_32x32x16_bf16 v[16:31], v[2:5], v[172:175], v[16:31]
	v_mfma_f32_32x32x16_bf16 v[32:47], v[2:5], v[176:179], v[32:47]
	s_cbranch_scc1 .LBB0_491
	s_branch .LBB0_449
; __device__ __forceinline__ unsigned cvtpk(float lo, float hi) { unsigned r; asm volatile("v_cvt_pk_bf16_f32 %0, %1, %2" : "=v"(r) : "v"(lo), "v"(hi)); return r; }
; __device__ __forceinline__ float xor1_(float v) { return __int_as_float(__builtin_amdgcn_update_dpp(0, __float_as_int(v), 0xB1, 0xf, 0xf, false)); }
; #define SBAR() __builtin_amdgcn_sched_barrier(0)
; __device__ __forceinline__ int crow(int r, int hi) { return (r & 3) + 8 * (r >> 2) + 4 * hi; }
; #define A3_BAR() do { asm volatile("s_waitcnt vmcnt(0) lgkmcnt(0)" ::: "memory"); __builtin_amdgcn_s_barrier(); asm volatile("" ::: "memory"); } while (0)
; __device__ __forceinline__ void partialSM(f32x16& p0, f32x16& p1, float& m_reg, float& mn, float& alpha) {
;     ...
;     if (__builtin_expect(__all((pmax - m_reg) * SM_SCALE <= THR), 1)) { mn = m_reg; alpha = 1.f; }
;     else { mn = fmaxf(m_reg, pmax); alpha = __builtin_amdgcn_exp2f((m_reg - mn) * C2); m_reg = mn; }
; __device__ __forceinline__ void attn_block3(const BlockRef& cur, char* lds, const int wid) {
;     ...
;         if (__any(alpha < 1.f)) { if (hi == 0) al_l[r32] = alpha; asm volatile("s_waitcnt lgkmcnt(0)" ::: "memory");
; #pragma unroll
;             for (int d_ = 0; d_ < 4; ++d_)
; #pragma unroll
;                 for (int r = 0; r < 16; ++r) { const float f_ = al_l[crow(r, hi)]; o[d_][r] *= f_; o2[d_][r] *= f_; } }
;         finishSM(p0, p1, alpha, l_reg, pa0, pa1, pa2, pa3); SBAR();
;         pv_tile2(o, o2, vbase + (t & 1) * 2 * SHM_V, pa0, pa1, pa2, pa3);
;         A3_BAR();
;     }
;     if (hi == 0) li_l[r32] = l_reg; asm volatile("s_waitcnt lgkmcnt(0)" ::: "memory");
; #pragma unroll
;     for (int r = 0; r < 16; ++r) { const int orow = crow(r, hi); const float rli = __builtin_amdgcn_rcpf(li_l[orow]);
;         const size_t ro = (size_t)(wid * QBLK + orow) * D;
; #pragma unroll
;         for (int d0 = 0; d0 < 4; ++d0) { const float v = o[d0][r] * rli, v2 = o2[d0][r] * rli; const float vn = xor1_(v), vn2 = xor1_(v2);
;             if ((r32 & 1) == 0) { __builtin_nontemporal_store(cvtpk(v, vn), (unsigned*)(cur.O + ro + d0 * 32 + r32)); __builtin_nontemporal_store(cvtpk(v2, vn2), (unsigned*)(cur.O2 + ro + d0 * 32 + r32)); } } }
.Ldiff_slow:
	v_max_f32_e32 v14, v249, v0
	v_sub_f32_e32 v0, v249, v14
	v_mul_f32_e32 v0, 0x3e0293ee, v0
	v_exp_f32_e32 v0, v0
	s_nop 0
	v_cmp_gt_f32_e32 vcc, 1.0, v0
	s_cbranch_vccz .Ldiff_slow_nr
	s_and_saveexec_b64 s[70:71], s[4:5]
	ds_write_b32 v241, v0 offset:128
	s_or_b64 exec, exec, s[70:71]
	s_waitcnt lgkmcnt(0)
	ds_read_b128 v[176:179], v237 offset:224
	ds_read_b128 v[10:13], v237 offset:192
	ds_read_b128 v[6:9], v237 offset:160
	ds_read_b128 v[2:5], v237 offset:128
	s_waitcnt lgkmcnt(0)
	v_pk_mul_f32 v[126:127], v[126:127], v[178:179]
	v_pk_mul_f32 v[122:123], v[122:123], v[12:13]
	v_pk_mul_f32 v[118:119], v[118:119], v[8:9]
	v_pk_mul_f32 v[114:115], v[114:115], v[4:5]
	v_pk_mul_f32 v[124:125], v[124:125], v[176:177]
	v_pk_mul_f32 v[120:121], v[120:121], v[10:11]
	v_pk_mul_f32 v[116:117], v[116:117], v[6:7]
	v_pk_mul_f32 v[112:113], v[112:113], v[2:3]
	v_pk_mul_f32 v[142:143], v[142:143], v[178:179]
	v_pk_mul_f32 v[138:139], v[138:139], v[12:13]
	v_pk_mul_f32 v[134:135], v[134:135], v[8:9]
	v_pk_mul_f32 v[130:131], v[130:131], v[4:5]
	v_pk_mul_f32 v[140:141], v[140:141], v[176:177]
	v_pk_mul_f32 v[136:137], v[136:137], v[10:11]
	v_pk_mul_f32 v[132:133], v[132:133], v[6:7]
	v_pk_mul_f32 v[128:129], v[128:129], v[2:3]
	v_pk_mul_f32 v[94:95], v[94:95], v[178:179]
	v_pk_mul_f32 v[90:91], v[90:91], v[12:13]
	v_pk_mul_f32 v[86:87], v[86:87], v[8:9]
	v_pk_mul_f32 v[82:83], v[82:83], v[4:5]
	v_pk_mul_f32 v[92:93], v[92:93], v[176:177]
	v_pk_mul_f32 v[88:89], v[88:89], v[10:11]
	v_pk_mul_f32 v[84:85], v[84:85], v[6:7]
	v_pk_mul_f32 v[80:81], v[80:81], v[2:3]
	v_pk_mul_f32 v[110:111], v[110:111], v[178:179]
	v_pk_mul_f32 v[106:107], v[106:107], v[12:13]
	v_pk_mul_f32 v[102:103], v[102:103], v[8:9]
	v_pk_mul_f32 v[98:99], v[98:99], v[4:5]
	v_pk_mul_f32 v[108:109], v[108:109], v[176:177]
	v_pk_mul_f32 v[104:105], v[104:105], v[10:11]
	v_pk_mul_f32 v[100:101], v[100:101], v[6:7]
	v_pk_mul_f32 v[96:97], v[96:97], v[2:3]
	v_pk_mul_f32 v[62:63], v[62:63], v[178:179]
	v_pk_mul_f32 v[58:59], v[58:59], v[12:13]
	v_pk_mul_f32 v[54:55], v[54:55], v[8:9]
	v_pk_mul_f32 v[50:51], v[50:51], v[4:5]
	v_pk_mul_f32 v[60:61], v[60:61], v[176:177]
	v_pk_mul_f32 v[56:57], v[56:57], v[10:11]
	v_pk_mul_f32 v[52:53], v[52:53], v[6:7]
	v_pk_mul_f32 v[48:49], v[48:49], v[2:3]
	v_pk_mul_f32 v[78:79], v[78:79], v[178:179]
	v_pk_mul_f32 v[74:75], v[74:75], v[12:13]
	v_pk_mul_f32 v[70:71], v[70:71], v[8:9]
	v_pk_mul_f32 v[66:67], v[66:67], v[4:5]
	v_pk_mul_f32 v[76:77], v[76:77], v[176:177]
	v_pk_mul_f32 v[72:73], v[72:73], v[10:11]
	v_pk_mul_f32 v[68:69], v[68:69], v[6:7]
	v_pk_mul_f32 v[64:65], v[64:65], v[2:3]
	v_pk_mul_f32 v[30:31], v[30:31], v[178:179]
	v_pk_mul_f32 v[26:27], v[26:27], v[12:13]
	v_pk_mul_f32 v[22:23], v[22:23], v[8:9]
	v_pk_mul_f32 v[18:19], v[18:19], v[4:5]
	v_pk_mul_f32 v[28:29], v[28:29], v[176:177]
	v_pk_mul_f32 v[24:25], v[24:25], v[10:11]
	v_pk_mul_f32 v[20:21], v[20:21], v[6:7]
	v_pk_mul_f32 v[16:17], v[16:17], v[2:3]
	v_pk_mul_f32 v[46:47], v[46:47], v[178:179]
	v_pk_mul_f32 v[42:43], v[42:43], v[12:13]
	v_pk_mul_f32 v[38:39], v[38:39], v[8:9]
	v_pk_mul_f32 v[34:35], v[34:35], v[4:5]
	v_pk_mul_f32 v[44:45], v[44:45], v[176:177]
	v_pk_mul_f32 v[40:41], v[40:41], v[10:11]
	v_pk_mul_f32 v[36:37], v[36:37], v[6:7]
	v_pk_mul_f32 v[32:33], v[32:33], v[2:3]
.Ldiff_slow_nr:
	v_mov_b32_e32 v249, v14
	s_branch .Ldiff_join
.LBB0_491:
	s_and_saveexec_b64 s[6:7], s[4:5]
	ds_write_b32 v241, v250
	s_or_b64 exec, exec, s[6:7]
	s_waitcnt lgkmcnt(0)
	ds_read_b32 v0, v237
	s_lshl_b32 s4, s44, 15
	s_or_b32 s44, s4, s78
	s_lshl_b64 s[4:5], s[44:45], 1
	s_add_u32 s4, s30, s4
	s_waitcnt lgkmcnt(0)
	v_rcp_f32_e32 v4, v0
	s_addc_u32 s5, s31, s5
	v_or_b32_e32 v0, s39, v236
	s_add_u32 s6, s4, 0x400000
	v_and_b32_e32 v2, 1, v239
	v_lshlrev_b32_e32 v0, 7, v0
	v_mul_f32_e32 v7, v112, v4
	v_mul_f32_e32 v5, v128, v4
	v_mov_b32_e32 v8, 0
	v_mov_b32_e32 v6, 0
	s_addc_u32 s7, s5, 0
	v_cmp_eq_u32_e32 vcc, 0, v2
	v_mov_b32_dpp v8, v7 quad_perm:[1,0,3,2] row_mask:0xf bank_mask:0xf
	v_mov_b32_dpp v6, v5 quad_perm:[1,0,3,2] row_mask:0xf bank_mask:0xf
	v_lshlrev_b32_e32 v0, 1, v0
	v_lshlrev_b32_e32 v2, 1, v238
	s_and_saveexec_b64 s[68:69], vcc
	s_cbranch_execz .LBB0_495
	v_lshl_add_u64 v[10:11], s[6:7], 0, v[0:1]
	v_mov_b32_e32 v3, v1
	v_lshl_add_u64 v[12:13], s[4:5], 0, v[0:1]
	v_lshl_add_u64 v[10:11], v[10:11], 0, v[2:3]
	v_lshl_add_u64 v[12:13], v[12:13], 0, v[2:3]
	v_cvt_pk_bf16_f32 v3, v7, v8
	global_store_dword v[12:13], v3, off nt
	v_cvt_pk_bf16_f32 v3, v5, v6
	global_store_dword v[10:11], v3, off nt
